# P6/P7/P10: WGs with blockIdx bit3 run the skinny (sample-row) GEMM before the 256x256 tile GEMM so epilogue bursts of the two halves interleave
# speedup vs baseline: 1.0123x; 1.0105x over previous
; #define LAS __attribute__((address_space(3)))
; #define SEAM(k) do { if ((k) + 1 < hi) xcd_barrier(xbar); } while (0)
;     __device__ bool next(int i, Unit& u) const {
;         long L = (long)i * G + c; if (L >= (long)nwg * rep) return false;
;         L %= nwg;
;         int wgid = (int)L; { const int q = nwg / NXCD, r = nwg % NXCD, xcd = wgid % NXCD, off = wgid / NXCD; wgid = (xcd < r ? xcd * (q + 1) : r * (q + 1) + (xcd - r) * q) + off; }
;         const int nig = WGM * nN, gid = wgid / nig, fm = gid * WGM, gsz = (nM - fm) < WGM ? (nM - fm) : WGM;
;         u.pm = fm + ((wgid % nig) % gsz); u.pn = (wgid % nig) / gsz; return true;
;     }
; __global__ void __launch_bounds__(512, 2) fwd(Params P) {
;     ...
;     if (IN(7)) for (int rep_ = 0; rep_ < NREP(7); ++rep_) { pg8::Gemm g{(const bf16_t*)(ws + O_MIX), (const bf16_t*)(ws + O_WOUTT), ROW_S, D, D}; pg8::StaticOrder S; S.init(ROW_S, D, gridDim.x, blockIdx.x);
;         EpiRes E{P.in[0], P.in[1], nullptr, 0, (bf16_t*)(ws + O_R)}; pg8::gemm_phase<EpiRes>((LAS unsigned char*)shm, g, S, E); skinny_phase<1>(P, shm); SEAM(7); }
.LBB0_990:
	s_cmp_lt_i32 s14, 8
	s_cselect_b64 s[0:1], -1, 0
	s_cmp_gt_i32 s15, 7
	s_cselect_b64 s[2:3], -1, 0
	s_and_b64 s[0:1], s[0:1], s[2:3]
	s_andn2_b64 vcc, exec, s[0:1]
	s_cbranch_vccnz .LBB0_1080
	s_bitcmp0_b32 s94, 3
	s_cbranch_scc1 .Lp7_gemm
	v_and_b32_e32 v206, 15, v214
	s_add_u32 s4, s12, 0x1a142000
	s_addc_u32 s5, s13, 0
	s_add_u32 s6, s12, 0xe3c2000
	s_addc_u32 s7, s13, 0
	s_add_u32 s8, s12, 0x18042000
	s_addc_u32 s9, s13, 0
	s_branch .Lsk1_entry
.Lp7_gemm:
	s_cmpk_lt_i32 s94, 0x100
	s_cselect_b64 s[2:3], -1, 0
	s_cmpk_gt_i32 s94, 0xff
	v_readfirstlane_b32 s17, v214
	s_cbranch_scc1 .LBB0_993
	s_ashr_i32 s0, s94, 31
	s_lshr_b32 s0, s0, 24
	s_add_i32 s0, s94, s0
	s_and_b32 s0, s0, 0xff00
	s_sub_i32 s0, s94, s0
	s_sext_i32_i16 s1, s0
	s_bfe_u32 s1, s1, 0x3001c
	s_add_i32 s1, s0, s1
	s_sext_i32_i16 s4, s1
	s_and_b32 s1, s1, 0xfff8
	s_sub_i32 s0, s0, s1
	s_ashr_i32 s4, s4, 3
	s_mul_i32 s1, s0, 33
	s_lshl_b32 s5, s0, 5
	s_sext_i32_i16 s0, s0
	s_cmp_lt_i32 s0, 0
	s_cselect_b32 s0, s1, s5
	s_add_i32 s0, s0, s4
	s_sext_i32_i16 s1, s0
	s_bfe_u32 s1, s1, 0x60019
	s_add_i32 s1, s0, s1
	s_sext_i32_i16 s4, s1
	s_and_b32 s1, s1, 0xffc0
	s_sub_i32 s0, s0, s1
	s_bfe_i32 s1, s0, 0x80000
	s_bfe_u32 s1, s1, 0x3000c
	s_add_i32 s1, s0, s1
	s_bfe_i32 s5, s1, 0x80000
	s_and_b32 s1, s1, 0xf8
	s_ashr_i32 s4, s4, 6
	s_sub_i32 s0, s0, s1
	s_lshl_b32 s4, s4, 3
	s_sext_i32_i16 s5, s5
	s_sext_i32_i8 s0, s0
	s_add_i32 s26, s4, s0
	s_ashr_i32 s0, s5, 3

; #define PG8_WAIT_V(n) asm volatile("s_waitcnt vmcnt(" #n ")" ::: "memory")
; #define PG8_BAR __builtin_amdgcn_s_barrier()
; template <class Epi>
; __device__ __forceinline__ void gemm_phase(LAS unsigned char* lds, const Gemm g, const StaticOrder& S, const Epi& E) {
;     ...
;     PG8_WAIT_V(0);
;     if (wr == 0) PG8_BAR;
;     PG8_BAR;
; template <int MODE>
; __device__ __forceinline__ void skinny_phase(const Params& P, unsigned char* shm) {
;     ...
;     for (int tile = blockIdx.x; tile < 256; tile += gridDim.x) {
;         const int mt = tile & 3, nt = tile >> 2;
;         const bf16_t* A; const bf16_t* Bt; int ld, k0, nks;
;         if (MODE == 0) { const int half = wave >> 2; A = (const bf16_t*)(ws + (half ? O_YB : O_YA)); Bt = (const bf16_t*)(ws + (half ? O_WBT : O_WAT)); ld = 1024; nks = 8; k0 = (wave & 3) * 256; }
;         else if (MODE == 1) { A = (const bf16_t*)(ws + O_MIX); Bt = (const bf16_t*)(ws + O_WOUTT); ld = 2048; nks = 8; k0 = wave * 256; }
;         else { A = (const bf16_t*)(ws + O_HFF); Bt = (const bf16_t*)(ws + O_WDT); ld = DFF; nks = 22; k0 = wave * 704; }
;         const bf16_t* ap = A + (size_t)(ROW_S + 32 * mt + l16) * ld + k0 + 8 * q; const bf16_t* bp = Bt + (size_t)(32 * nt + l16) * ld + k0 + 8 * q;
.LBB0_1022:
	s_waitcnt vmcnt(0)
	s_cmpk_gt_u32 s17, 0xff
	s_cbranch_scc1 .LBB0_1024
	s_barrier
.LBB0_1024:
	s_bitcmp1_b32 s94, 3
	s_cbranch_scc1 .LBB0_1026
.Lsk1_entry:
	v_bfe_u32 v10, v214, 4, 2
	v_lshlrev_b32_e32 v0, 9, v215
	v_mov_b32_e32 v1, 0
	v_lshl_add_u64 v[2:3], s[8:9], 0, v[0:1]
	v_lshlrev_b32_e32 v4, 4, v10
	v_mov_b32_e32 v5, v1
	v_lshl_add_u64 v[8:9], s[6:7], 0, v[0:1]
	v_lshlrev_b32_e32 v7, 2, v206
	v_lshl_add_u64 v[2:3], v[2:3], 0, v[4:5]
	v_lshl_add_u64 v[4:5], v[8:9], 0, v[4:5]
	v_lshlrev_b32_e32 v8, 12, v215
	v_lshlrev_b32_e32 v0, 9, v10
	v_add3_u32 v9, 0, v7, v8
	v_lshlrev_b32_e32 v7, 1, v214
	v_add_u32_e32 v9, v9, v0
	v_lshrrev_b32_e32 v6, 4, v214
	v_and_b32_e32 v7, 30, v7
	v_lshl_add_u32 v8, v214, 3, 0
	s_lshl_b32 s2, s94, 3
	s_lshl_b32 s3, s96, 3
	s_lshl_b32 s6, s94, 5
	s_lshl_b32 s7, s96, 5
	s_mov_b32 s8, 0x10000
	s_brev_b32 s9, 63
	v_add_u32_e32 v10, 0x800, v9
	s_mov_b32 s10, s94
	s_barrier
; template <int MODE>
; __device__ __forceinline__ void skinny_phase(const Params& P, unsigned char* shm) {
;     ...
;     for (int tile = blockIdx.x; tile < 256; tile += gridDim.x) {
;         const int mt = tile & 3, nt = tile >> 2;
;         const bf16_t* A; const bf16_t* Bt; int ld, k0, nks;
;         if (MODE == 0) { const int half = wave >> 2; A = (const bf16_t*)(ws + (half ? O_YB : O_YA)); Bt = (const bf16_t*)(ws + (half ? O_WBT : O_WAT)); ld = 1024; nks = 8; k0 = (wave & 3) * 256; }
;         else if (MODE == 1) { A = (const bf16_t*)(ws + O_MIX); Bt = (const bf16_t*)(ws + O_WOUTT); ld = 2048; nks = 8; k0 = wave * 256; }
;         else { A = (const bf16_t*)(ws + O_HFF); Bt = (const bf16_t*)(ws + O_WDT); ld = DFF; nks = 22; k0 = wave * 704; }
;         const bf16_t* ap = A + (size_t)(ROW_S + 32 * mt + l16) * ld + k0 + 8 * q; const bf16_t* bp = Bt + (size_t)(32 * nt + l16) * ld + k0 + 8 * q;
;         f32x4 acc[2][2];
; #pragma unroll
;         for (int i = 0; i < 2; ++i) { acc[i][0] = (f32x4){0.f, 0.f, 0.f, 0.f}; acc[i][1] = (f32x4){0.f, 0.f, 0.f, 0.f}; }
; #pragma unroll 8
;         for (int ks = 0; ks < nks; ++ks) { const bf16x8 a0 = *(const bf16x8*)(ap + 32 * ks), a1 = *(const bf16x8*)(ap + (size_t)16 * ld + 32 * ks), b0 = *(const bf16x8*)(bp + 32 * ks), b1 = *(const bf16x8*)(bp + (size_t)16 * ld + 32 * ks);
;             acc[0][0] = mfma16(a0, b0, acc[0][0]); acc[0][1] = mfma16(a0, b1, acc[0][1]); acc[1][0] = mfma16(a1, b0, acc[1][0]); acc[1][1] = mfma16(a1, b1, acc[1][1]); }
;         MFMA_SETTLE();
; #pragma unroll
;         for (int mi = 0; mi < 2; ++mi)
; #pragma unroll
;             for (int ni = 0; ni < 2; ++ni)
; #pragma unroll
;                 for (int r = 0; r < 4; ++r) red[wave * 1024 + (16 * mi + 4 * q + r) * 32 + 16 * ni + l16] = acc[mi][ni][r];
;         __syncthreads();
;         { const int e = tid * 2, rr = e >> 5, cc = e & 31; const int row = ROW_S + 32 * mt + rr, col = 32 * nt + cc;
;           float s0 = 0.f, s1 = 0.f, u0 = 0.f, u1 = 0.f;
; #pragma unroll
;           for (int w = 0; w < 4; ++w) { const f32x2 x = *(const f32x2*)(red + w * 1024 + e), y = *(const f32x2*)(red + (4 + w) * 1024 + e); s0 += x.x; s1 += x.y; u0 += y.x; u1 += y.y; }
;           if (MODE == 0) { const bf16_t* gp = (const bf16_t*)(ws + O_PROJ) + (size_t)row * NPROJ + col;
.LBB0_1025:
	s_and_b32 s0, s6, 0x60
	s_or_b32 s11, s0, 0x2000
	v_or_b32_e32 v0, s11, v206
	v_lshlrev_b32_e32 v0, 12, v0
	s_and_b32 s16, s2, 0xffffffe0
	v_lshl_add_u64 v[56:57], v[2:3], 0, v[0:1]
	v_or_b32_e32 v16, s16, v206
	v_ashrrev_i32_e32 v17, 31, v16
	v_lshlrev_b64 v[16:17], 12, v[16:17]
	v_lshl_add_u64 v[58:59], v[4:5], 0, v[16:17]
	v_add_co_u32_e32 v60, vcc, s8, v56
	s_nop 1
	v_addc_co_u32_e32 v61, vcc, 0, v57, vcc
	v_add_co_u32_e32 v62, vcc, s8, v58
	s_nop 1
	v_addc_co_u32_e32 v63, vcc, 0, v59, vcc
	global_load_dwordx4 v[66:69], v[56:57], off
	global_load_dwordx4 v[70:73], v[58:59], off
	global_load_dwordx4 v[74:77], v[60:61], off
	global_load_dwordx4 v[78:81], v[62:63], off
	global_load_dwordx4 v[82:85], v[56:57], off offset:64
	global_load_dwordx4 v[86:89], v[58:59], off offset:64
	global_load_dwordx4 v[90:93], v[60:61], off offset:64
	global_load_dwordx4 v[94:97], v[62:63], off offset:64
	global_load_dwordx4 v[98:101], v[56:57], off offset:128
	global_load_dwordx4 v[102:105], v[58:59], off offset:128
	global_load_dwordx4 v[106:109], v[60:61], off offset:128
	global_load_dwordx4 v[110:113], v[62:63], off offset:128
	global_load_dwordx4 v[114:117], v[56:57], off offset:192
	global_load_dwordx4 v[118:121], v[58:59], off offset:192
	global_load_dwordx4 v[122:125], v[60:61], off offset:192
	global_load_dwordx4 v[128:131], v[62:63], off offset:192
	global_load_dwordx4 v[132:135], v[56:57], off offset:256
	global_load_dwordx4 v[136:139], v[58:59], off offset:256
	global_load_dwordx4 v[140:143], v[60:61], off offset:256
	global_load_dwordx4 v[144:147], v[62:63], off offset:256
	global_load_dwordx4 v[148:151], v[56:57], off offset:320
	global_load_dwordx4 v[152:155], v[58:59], off offset:320
	global_load_dwordx4 v[156:159], v[60:61], off offset:320
	global_load_dwordx4 v[160:163], v[62:63], off offset:320
	global_load_dwordx4 v[164:167], v[56:57], off offset:384
	global_load_dwordx4 v[168:171], v[58:59], off offset:384
	global_load_dwordx4 v[172:175], v[60:61], off offset:384
	global_load_dwordx4 v[194:197], v[62:63], off offset:384
	global_load_dwordx4 v[198:201], v[56:57], off offset:448
	global_load_dwordx4 v[28:31], v[58:59], off offset:448
	global_load_dwordx4 v[32:35], v[60:61], off offset:448
	global_load_dwordx4 v[36:39], v[62:63], off offset:448
	s_waitcnt vmcnt(28)
	v_mfma_f32_16x16x32_bf16 v[24:27], v[66:69], v[70:73], 0
	v_mfma_f32_16x16x32_bf16 v[12:15], v[66:69], v[78:81], 0
	v_mfma_f32_16x16x32_bf16 v[16:19], v[74:77], v[70:73], 0
	v_mfma_f32_16x16x32_bf16 v[20:23], v[74:77], v[78:81], 0
	s_waitcnt vmcnt(24)
	v_mfma_f32_16x16x32_bf16 v[24:27], v[82:85], v[86:89], v[24:27]
	v_mfma_f32_16x16x32_bf16 v[12:15], v[82:85], v[94:97], v[12:15]
	v_mfma_f32_16x16x32_bf16 v[16:19], v[90:93], v[86:89], v[16:19]
	v_mfma_f32_16x16x32_bf16 v[20:23], v[90:93], v[94:97], v[20:23]
	s_waitcnt vmcnt(20)
	v_mfma_f32_16x16x32_bf16 v[24:27], v[98:101], v[102:105], v[24:27]
	v_mfma_f32_16x16x32_bf16 v[12:15], v[98:101], v[110:113], v[12:15]
	v_mfma_f32_16x16x32_bf16 v[16:19], v[106:109], v[102:105], v[16:19]
	v_mfma_f32_16x16x32_bf16 v[20:23], v[106:109], v[110:113], v[20:23]
	s_waitcnt vmcnt(16)
	v_mfma_f32_16x16x32_bf16 v[24:27], v[114:117], v[118:121], v[24:27]
	v_mfma_f32_16x16x32_bf16 v[12:15], v[114:117], v[128:131], v[12:15]
	v_mfma_f32_16x16x32_bf16 v[16:19], v[122:125], v[118:121], v[16:19]
	v_mfma_f32_16x16x32_bf16 v[20:23], v[122:125], v[128:131], v[20:23]
	s_waitcnt vmcnt(12)
	v_mfma_f32_16x16x32_bf16 v[24:27], v[132:135], v[136:139], v[24:27]
	v_mfma_f32_16x16x32_bf16 v[12:15], v[132:135], v[144:147], v[12:15]
	v_mfma_f32_16x16x32_bf16 v[16:19], v[140:143], v[136:139], v[16:19]
	v_mfma_f32_16x16x32_bf16 v[20:23], v[140:143], v[144:147], v[20:23]
	s_waitcnt vmcnt(8)
	v_mfma_f32_16x16x32_bf16 v[24:27], v[148:151], v[152:155], v[24:27]
	v_mfma_f32_16x16x32_bf16 v[12:15], v[148:151], v[160:163], v[12:15]
	v_mfma_f32_16x16x32_bf16 v[16:19], v[156:159], v[152:155], v[16:19]
	v_mfma_f32_16x16x32_bf16 v[20:23], v[156:159], v[160:163], v[20:23]
	s_waitcnt vmcnt(4)
	v_mfma_f32_16x16x32_bf16 v[24:27], v[164:167], v[168:171], v[24:27]
	v_mfma_f32_16x16x32_bf16 v[12:15], v[164:167], v[194:197], v[12:15]
	v_mfma_f32_16x16x32_bf16 v[16:19], v[172:175], v[168:171], v[16:19]
	v_mfma_f32_16x16x32_bf16 v[20:23], v[172:175], v[194:197], v[20:23]
	s_waitcnt vmcnt(0)
	v_mfma_f32_16x16x32_bf16 v[24:27], v[198:201], v[28:31], v[24:27]
	v_mfma_f32_16x16x32_bf16 v[12:15], v[198:201], v[36:39], v[12:15]
	v_mfma_f32_16x16x32_bf16 v[16:19], v[32:35], v[28:31], v[16:19]
	v_mfma_f32_16x16x32_bf16 v[20:23], v[32:35], v[36:39], v[20:23]
	s_nop 15
	s_nop 15
	v_add_u32_e32 v11, s11, v6
	v_or_b32_e32 v28, s16, v7
	v_lshlrev_b32_e32 v0, 13, v11
	s_nop 1
	ds_write2_b32 v9, v24, v12 offset1:16
	ds_write2_b32 v9, v25, v13 offset0:32 offset1:48
	ds_write2_b32 v9, v26, v14 offset0:64 offset1:80
	ds_write2_b32 v9, v27, v15 offset0:96 offset1:112
	ds_write2_b32 v10, v16, v20 offset1:16
	ds_write2_b32 v10, v17, v21 offset0:32 offset1:48
	ds_write2_b32 v10, v18, v22 offset0:64 offset1:80
	ds_write2_b32 v10, v19, v23 offset0:96 offset1:112
	v_lshl_add_u64 v[12:13], s[38:39], 0, v[0:1]
	v_ashrrev_i32_e32 v29, 31, v28
	v_lshl_add_u64 v[12:13], v[28:29], 2, v[12:13]
	v_add_co_u32_e32 v12, vcc, s9, v12
	s_waitcnt lgkmcnt(0)
	s_nop 0
	v_addc_co_u32_e32 v13, vcc, -1, v13, vcc
	s_barrier
	global_load_dwordx2 v[30:31], v[12:13], off
	ds_read2st64_b64 v[12:15], v8 offset1:8
	ds_read2st64_b64 v[16:19], v8 offset0:32 offset1:40
	ds_read2st64_b64 v[20:23], v8 offset0:16 offset1:24
	ds_read2st64_b64 v[24:27], v8 offset0:48 offset1:56
	v_lshlrev_b32_e32 v0, 12, v11
	v_lshl_add_u64 v[32:33], s[4:5], 0, v[0:1]
	v_lshl_add_u64 v[28:29], v[28:29], 1, v[32:33]
	s_waitcnt lgkmcnt(2)
	v_mov_b32_e32 v32, v16
	v_mov_b32_e32 v33, v12
	v_mov_b32_e32 v34, v18
	v_mov_b32_e32 v35, v14
	v_mov_b32_e32 v12, v17
	v_pk_add_f32 v[16:17], v[32:33], 0 op_sel_hi:[1,0]
	s_waitcnt lgkmcnt(0)
	v_mov_b32_e32 v36, v24
	v_mov_b32_e32 v37, v20
	v_mov_b32_e32 v14, v19
	v_pk_add_f32 v[12:13], v[12:13], 0 op_sel_hi:[1,0]
	v_pk_add_f32 v[16:17], v[16:17], v[34:35]
	v_mov_b32_e32 v38, v26
	v_mov_b32_e32 v39, v22
	v_mov_b32_e32 v20, v25
	v_pk_add_f32 v[12:13], v[12:13], v[14:15]
	v_pk_add_f32 v[14:15], v[16:17], v[36:37]
	v_mov_b32_e32 v22, v27
	v_pk_add_f32 v[12:13], v[12:13], v[20:21]
	v_pk_add_f32 v[14:15], v[14:15], v[38:39]
	s_add_i32 s10, s10, s96
	s_add_i32 s2, s2, s3
	s_add_i32 s6, s6, s7
	v_pk_add_f32 v[12:13], v[12:13], v[22:23]
	s_cmpk_lt_i32 s10, 0x100
	s_waitcnt vmcnt(0)
	v_fmamk_f32 v0, v30, 0x3f9837f0, v15
	v_fmamk_f32 v11, v31, 0x3f9837f0, v13
	v_add_f32_e32 v0, v14, v0
	v_add_f32_e32 v11, v12, v11
	v_cvt_pk_bf16_f32 v0, v0, v11
	global_store_dword v[28:29], v0, off
	s_barrier
	s_cbranch_scc1 .LBB0_1025
	s_bitcmp0_b32 s94, 3
	s_cbranch_scc1 .LBB0_1026
	s_branch .Lp7_gemm

; #define LAS __attribute__((address_space(3)))
; #define SEAM(k) do { if ((k) + 1 < hi) xcd_barrier(xbar); } while (0)
;     __device__ bool next(int i, Unit& u) const {
;         long L = (long)i * G + c; if (L >= (long)nwg * rep) return false;
;         L %= nwg;
;         int wgid = (int)L; { const int q = nwg / NXCD, r = nwg % NXCD, xcd = wgid % NXCD, off = wgid / NXCD; wgid = (xcd < r ? xcd * (q + 1) : r * (q + 1) + (xcd - r) * q) + off; }
;         const int nig = WGM * nN, gid = wgid / nig, fm = gid * WGM, gsz = (nM - fm) < WGM ? (nM - fm) : WGM;
;         u.pm = fm + ((wgid % nig) % gsz); u.pn = (wgid % nig) / gsz; return true;
; __global__ void __launch_bounds__(512, 2) fwd(Params P) {
;     ...
;     if (IN(10)) for (int rep_ = 0; rep_ < NREP(10); ++rep_) { pg8::Gemm g{(const bf16_t*)(ws + O_HFF), (const bf16_t*)(ws + O_WDT), ROW_S, D, DFF}; pg8::StaticOrder S; S.init(ROW_S, D, gridDim.x, blockIdx.x, GREP10);
;         EpiRes E{nullptr, nullptr, (const bf16_t*)(ws + O_X1B), 1, (bf16_t*)(ws + O_R)}; pg8::gemm_phase<EpiRes>((LAS unsigned char*)shm, g, S, E); skinny_phase<2>(P, shm); SEAM(10); }
.LBB0_1319:
	s_cmp_lt_i32 s14, 11
	s_cselect_b64 s[0:1], -1, 0
	s_cmp_gt_i32 s15, 10
	s_cselect_b64 s[2:3], -1, 0
	s_and_b64 s[0:1], s[0:1], s[2:3]
	s_andn2_b64 vcc, exec, s[0:1]
	s_cbranch_vccnz .LBB0_1413
	s_bitcmp0_b32 s94, 3
	s_cbranch_scc1 .Lp10_gemm
	v_and_b32_e32 v153, 15, v214
	s_add_u32 s6, s12, 0x1a142000
	s_addc_u32 s7, s13, 0
	s_add_u32 s8, s12, 0x117c2000
	s_addc_u32 s9, s13, 0
	s_add_u32 s10, s12, 0x4542000
	s_addc_u32 s11, s13, 0
	s_branch .Lsk2_entry
.Lp10_gemm:
	s_cmpk_lt_i32 s94, 0x100
	s_cselect_b64 s[0:1], -1, 0
	s_cmpk_gt_i32 s94, 0xff
	v_readfirstlane_b32 s19, v214
	s_cbranch_scc1 .LBB0_1322
	s_ashr_i32 s2, s94, 31
	s_lshr_b32 s2, s2, 24
	s_add_i32 s2, s94, s2
	s_and_b32 s2, s2, 0xff00
	s_sub_i32 s2, s94, s2
	s_sext_i32_i16 s3, s2
	s_bfe_u32 s3, s3, 0x3001c
	s_add_i32 s3, s2, s3
	s_sext_i32_i16 s4, s3
	s_and_b32 s3, s3, 0xfff8
	s_sub_i32 s2, s2, s3
	s_ashr_i32 s4, s4, 3
	s_mul_i32 s3, s2, 33
	s_lshl_b32 s5, s2, 5
	s_sext_i32_i16 s2, s2
	s_cmp_lt_i32 s2, 0
	s_cselect_b32 s2, s3, s5
	s_add_i32 s2, s2, s4
	s_sext_i32_i16 s3, s2
	s_bfe_u32 s3, s3, 0x60019
	s_add_i32 s3, s2, s3
	s_sext_i32_i16 s4, s3
	s_and_b32 s3, s3, 0xffc0
	s_sub_i32 s2, s2, s3
	s_bfe_i32 s3, s2, 0x80000
	s_bfe_u32 s3, s3, 0x3000c
	s_add_i32 s3, s2, s3
	s_bfe_i32 s5, s3, 0x80000
	s_and_b32 s3, s3, 0xf8
	s_ashr_i32 s4, s4, 6
	s_sub_i32 s2, s2, s3
	s_lshl_b32 s4, s4, 3
	s_sext_i32_i16 s5, s5
	s_sext_i32_i8 s2, s2
	s_add_i32 s50, s4, s2
	s_ashr_i32 s49, s5, 3

; __device__ __forceinline__ f32x4 mfma16(bf16x8 a, bf16x8 b, f32x4 c) { return __builtin_amdgcn_mfma_f32_16x16x32_bf16(a, b, c, 0, 0, 0); }
; template <int MODE>
; __device__ __forceinline__ void skinny_phase(const Params& P, unsigned char* shm) {
;     ...
;     for (int tile = blockIdx.x; tile < 256; tile += gridDim.x) {
;         const int mt = tile & 3, nt = tile >> 2;
;         const bf16_t* A; const bf16_t* Bt; int ld, k0, nks;
;         if (MODE == 0) { const int half = wave >> 2; A = (const bf16_t*)(ws + (half ? O_YB : O_YA)); Bt = (const bf16_t*)(ws + (half ? O_WBT : O_WAT)); ld = 1024; nks = 8; k0 = (wave & 3) * 256; }
;         else if (MODE == 1) { A = (const bf16_t*)(ws + O_MIX); Bt = (const bf16_t*)(ws + O_WOUTT); ld = 2048; nks = 8; k0 = wave * 256; }
;         else { A = (const bf16_t*)(ws + O_HFF); Bt = (const bf16_t*)(ws + O_WDT); ld = DFF; nks = 22; k0 = wave * 704; }
;         const bf16_t* ap = A + (size_t)(ROW_S + 32 * mt + l16) * ld + k0 + 8 * q; const bf16_t* bp = Bt + (size_t)(32 * nt + l16) * ld + k0 + 8 * q;
;         f32x4 acc[2][2];
; #pragma unroll
;         for (int i = 0; i < 2; ++i) { acc[i][0] = (f32x4){0.f, 0.f, 0.f, 0.f}; acc[i][1] = (f32x4){0.f, 0.f, 0.f, 0.f}; }
; #pragma unroll 8
;         for (int ks = 0; ks < nks; ++ks) { const bf16x8 a0 = *(const bf16x8*)(ap + 32 * ks), a1 = *(const bf16x8*)(ap + (size_t)16 * ld + 32 * ks), b0 = *(const bf16x8*)(bp + 32 * ks), b1 = *(const bf16x8*)(bp + (size_t)16 * ld + 32 * ks);
;             acc[0][0] = mfma16(a0, b0, acc[0][0]); acc[0][1] = mfma16(a0, b1, acc[0][1]); acc[1][0] = mfma16(a1, b0, acc[1][0]); acc[1][1] = mfma16(a1, b1, acc[1][1]); }
.LBB0_1355:
	s_waitcnt vmcnt(0)
	s_cmpk_gt_u32 s19, 0xff
	s_cbranch_scc1 .LBB0_1357
	s_barrier
.LBB0_1357:
	s_bitcmp1_b32 s94, 3
	s_cbranch_scc1 .LBB0_1359
.Lsk2_entry:
	v_mul_u32_u24_e32 v0, 0x2c0, v215
	v_bfe_u32 v9, v214, 4, 2
	v_lshlrev_b32_e32 v0, 1, v0
	v_mov_b32_e32 v1, 0
	v_lshl_add_u64 v[2:3], s[10:11], 0, v[0:1]
	v_lshlrev_b32_e32 v4, 4, v9
	v_mov_b32_e32 v5, v1
	v_lshl_add_u64 v[6:7], s[8:9], 0, v[0:1]
	v_lshlrev_b32_e32 v8, 2, v153
	v_lshl_add_u64 v[2:3], v[2:3], 0, v[4:5]
	v_lshl_add_u64 v[4:5], v[6:7], 0, v[4:5]
	v_lshlrev_b32_e32 v6, 12, v215
	v_lshlrev_b32_e32 v0, 9, v9
	v_add3_u32 v6, 0, v8, v6
	v_lshlrev_b32_e32 v7, 1, v214
	v_add_u32_e32 v17, v6, v0
	v_lshrrev_b32_e32 v14, 4, v214
	v_and_b32_e32 v15, 30, v7
	v_lshl_add_u32 v16, v214, 3, 0
	s_lshl_b32 s2, s94, 3
	s_lshl_b32 s3, s96, 3
	s_lshl_b32 s4, s94, 5
	s_lshl_b32 s5, s96, 5
	s_movk_i32 s8, 0x2c00
	v_add_u32_e32 v18, 0x800, v17
	s_barrier
.LBB0_1358:
	s_and_b32 s9, s4, 0x60
	s_bitset1_b32 s9, 13
	v_or_b32_e32 v0, s9, v153
	v_mul_u32_u24_e32 v0, 0x1600, v0
	v_lshlrev_b32_e32 v0, 1, v0
	v_lshl_add_u64 v[56:57], v[2:3], 0, v[0:1]
	s_and_b32 s10, s2, 0xffffffe0
	v_or_b32_e32 v0, s10, v153
	v_mad_i64_i32 v[58:59], s[0:1], v0, s8, v[4:5]
	v_add_co_u32_e32 v60, vcc, 0x2c000, v56
	s_nop 1
	v_addc_co_u32_e32 v61, vcc, 0, v57, vcc
	v_add_co_u32_e32 v62, vcc, 0x2c000, v58
	s_nop 1
	v_addc_co_u32_e32 v63, vcc, 0, v59, vcc
	global_load_dwordx4 v[66:69], v[56:57], off
	global_load_dwordx4 v[70:73], v[58:59], off
	global_load_dwordx4 v[74:77], v[60:61], off
	global_load_dwordx4 v[78:81], v[62:63], off
	global_load_dwordx4 v[82:85], v[56:57], off offset:64
	global_load_dwordx4 v[86:89], v[58:59], off offset:64
	global_load_dwordx4 v[90:93], v[60:61], off offset:64
	global_load_dwordx4 v[94:97], v[62:63], off offset:64
	global_load_dwordx4 v[98:101], v[56:57], off offset:128
	global_load_dwordx4 v[102:105], v[58:59], off offset:128
	global_load_dwordx4 v[106:109], v[60:61], off offset:128
	global_load_dwordx4 v[110:113], v[62:63], off offset:128
	global_load_dwordx4 v[114:117], v[56:57], off offset:192
	global_load_dwordx4 v[118:121], v[58:59], off offset:192
	global_load_dwordx4 v[122:125], v[60:61], off offset:192
	global_load_dwordx4 v[128:131], v[62:63], off offset:192
	global_load_dwordx4 v[132:135], v[56:57], off offset:256
	global_load_dwordx4 v[136:139], v[58:59], off offset:256
	global_load_dwordx4 v[140:143], v[60:61], off offset:256
	global_load_dwordx4 v[144:147], v[62:63], off offset:256
	global_load_dwordx4 v[148:151], v[56:57], off offset:320
	global_load_dwordx4 v[170:173], v[58:59], off offset:320
	global_load_dwordx4 v[174:177], v[60:61], off offset:320
	global_load_dwordx4 v[178:181], v[62:63], off offset:320
	global_load_dwordx4 v[188:191], v[56:57], off offset:384
	global_load_dwordx4 v[192:195], v[58:59], off offset:384
	global_load_dwordx4 v[196:199], v[60:61], off offset:384
	global_load_dwordx4 v[200:203], v[62:63], off offset:384
	global_load_dwordx4 v[204:207], v[56:57], off offset:448
	global_load_dwordx4 v[208:211], v[58:59], off offset:448
	global_load_dwordx4 v[32:35], v[60:61], off offset:448
	global_load_dwordx4 v[36:39], v[62:63], off offset:448
	s_waitcnt vmcnt(28)
	v_mfma_f32_16x16x32_bf16 v[6:9], v[66:69], v[70:73], 0
	v_mfma_f32_16x16x32_bf16 v[20:23], v[66:69], v[78:81], 0
	v_mfma_f32_16x16x32_bf16 v[24:27], v[74:77], v[70:73], 0
	v_mfma_f32_16x16x32_bf16 v[10:13], v[74:77], v[78:81], 0
	global_load_dwordx4 v[66:69], v[56:57], off offset:512
	global_load_dwordx4 v[70:73], v[58:59], off offset:512
	global_load_dwordx4 v[74:77], v[60:61], off offset:512
	global_load_dwordx4 v[78:81], v[62:63], off offset:512
	s_waitcnt vmcnt(28)
	v_mfma_f32_16x16x32_bf16 v[6:9], v[82:85], v[86:89], v[6:9]
	v_mfma_f32_16x16x32_bf16 v[20:23], v[82:85], v[94:97], v[20:23]
	v_mfma_f32_16x16x32_bf16 v[24:27], v[90:93], v[86:89], v[24:27]
	v_mfma_f32_16x16x32_bf16 v[10:13], v[90:93], v[94:97], v[10:13]
	global_load_dwordx4 v[82:85], v[56:57], off offset:576
	global_load_dwordx4 v[86:89], v[58:59], off offset:576
	global_load_dwordx4 v[90:93], v[60:61], off offset:576
	global_load_dwordx4 v[94:97], v[62:63], off offset:576
	s_waitcnt vmcnt(28)
	v_mfma_f32_16x16x32_bf16 v[6:9], v[98:101], v[102:105], v[6:9]
	v_mfma_f32_16x16x32_bf16 v[20:23], v[98:101], v[110:113], v[20:23]
	v_mfma_f32_16x16x32_bf16 v[24:27], v[106:109], v[102:105], v[24:27]
	v_mfma_f32_16x16x32_bf16 v[10:13], v[106:109], v[110:113], v[10:13]
	global_load_dwordx4 v[98:101], v[56:57], off offset:640
	global_load_dwordx4 v[102:105], v[58:59], off offset:640
	global_load_dwordx4 v[106:109], v[60:61], off offset:640
	global_load_dwordx4 v[110:113], v[62:63], off offset:640
	s_waitcnt vmcnt(28)
	v_mfma_f32_16x16x32_bf16 v[6:9], v[114:117], v[118:121], v[6:9]
	v_mfma_f32_16x16x32_bf16 v[20:23], v[114:117], v[128:131], v[20:23]
	v_mfma_f32_16x16x32_bf16 v[24:27], v[122:125], v[118:121], v[24:27]
	v_mfma_f32_16x16x32_bf16 v[10:13], v[122:125], v[128:131], v[10:13]
	global_load_dwordx4 v[114:117], v[56:57], off offset:704
	global_load_dwordx4 v[118:121], v[58:59], off offset:704
	global_load_dwordx4 v[122:125], v[60:61], off offset:704
	global_load_dwordx4 v[128:131], v[62:63], off offset:704
	s_waitcnt vmcnt(28)
	v_mfma_f32_16x16x32_bf16 v[6:9], v[132:135], v[136:139], v[6:9]
	v_mfma_f32_16x16x32_bf16 v[20:23], v[132:135], v[144:147], v[20:23]
	v_mfma_f32_16x16x32_bf16 v[24:27], v[140:143], v[136:139], v[24:27]
	v_mfma_f32_16x16x32_bf16 v[10:13], v[140:143], v[144:147], v[10:13]
	global_load_dwordx4 v[132:135], v[56:57], off offset:768
	global_load_dwordx4 v[136:139], v[58:59], off offset:768
	global_load_dwordx4 v[140:143], v[60:61], off offset:768
	global_load_dwordx4 v[144:147], v[62:63], off offset:768
	s_waitcnt vmcnt(28)
; __device__ __forceinline__ f32x4 mfma16(bf16x8 a, bf16x8 b, f32x4 c) { return __builtin_amdgcn_mfma_f32_16x16x32_bf16(a, b, c, 0, 0, 0); }
; template <int MODE>
; __device__ __forceinline__ void skinny_phase(const Params& P, unsigned char* shm) {
;     ...
; #pragma unroll 8
;         for (int ks = 0; ks < nks; ++ks) { const bf16x8 a0 = *(const bf16x8*)(ap + 32 * ks), a1 = *(const bf16x8*)(ap + (size_t)16 * ld + 32 * ks), b0 = *(const bf16x8*)(bp + 32 * ks), b1 = *(const bf16x8*)(bp + (size_t)16 * ld + 32 * ks);
;             acc[0][0] = mfma16(a0, b0, acc[0][0]); acc[0][1] = mfma16(a0, b1, acc[0][1]); acc[1][0] = mfma16(a1, b0, acc[1][0]); acc[1][1] = mfma16(a1, b1, acc[1][1]); }
	v_mfma_f32_16x16x32_bf16 v[6:9], v[148:151], v[170:173], v[6:9]
	v_mfma_f32_16x16x32_bf16 v[20:23], v[148:151], v[178:181], v[20:23]
	v_mfma_f32_16x16x32_bf16 v[24:27], v[174:177], v[170:173], v[24:27]
	v_mfma_f32_16x16x32_bf16 v[10:13], v[174:177], v[178:181], v[10:13]
	global_load_dwordx4 v[148:151], v[56:57], off offset:832
	global_load_dwordx4 v[170:173], v[58:59], off offset:832
	global_load_dwordx4 v[174:177], v[60:61], off offset:832
	global_load_dwordx4 v[178:181], v[62:63], off offset:832
	s_waitcnt vmcnt(28)
	v_mfma_f32_16x16x32_bf16 v[6:9], v[188:191], v[192:195], v[6:9]
	v_mfma_f32_16x16x32_bf16 v[20:23], v[188:191], v[200:203], v[20:23]
	v_mfma_f32_16x16x32_bf16 v[24:27], v[196:199], v[192:195], v[24:27]
	v_mfma_f32_16x16x32_bf16 v[10:13], v[196:199], v[200:203], v[10:13]
	global_load_dwordx4 v[188:191], v[56:57], off offset:896
	global_load_dwordx4 v[192:195], v[58:59], off offset:896
	global_load_dwordx4 v[196:199], v[60:61], off offset:896
	global_load_dwordx4 v[200:203], v[62:63], off offset:896
	s_waitcnt vmcnt(28)
	v_mfma_f32_16x16x32_bf16 v[6:9], v[204:207], v[208:211], v[6:9]
	v_mfma_f32_16x16x32_bf16 v[20:23], v[204:207], v[36:39], v[20:23]
	v_mfma_f32_16x16x32_bf16 v[24:27], v[32:35], v[208:211], v[24:27]
	v_mfma_f32_16x16x32_bf16 v[10:13], v[32:35], v[36:39], v[10:13]
	global_load_dwordx4 v[204:207], v[56:57], off offset:960
	global_load_dwordx4 v[208:211], v[58:59], off offset:960
	global_load_dwordx4 v[32:35], v[60:61], off offset:960
	global_load_dwordx4 v[36:39], v[62:63], off offset:960
	s_waitcnt vmcnt(28)
	v_mfma_f32_16x16x32_bf16 v[6:9], v[66:69], v[70:73], v[6:9]
	v_mfma_f32_16x16x32_bf16 v[20:23], v[66:69], v[78:81], v[20:23]
	v_mfma_f32_16x16x32_bf16 v[24:27], v[74:77], v[70:73], v[24:27]
	v_mfma_f32_16x16x32_bf16 v[10:13], v[74:77], v[78:81], v[10:13]
	global_load_dwordx4 v[66:69], v[56:57], off offset:1024
	global_load_dwordx4 v[70:73], v[58:59], off offset:1024
	global_load_dwordx4 v[74:77], v[60:61], off offset:1024
	global_load_dwordx4 v[78:81], v[62:63], off offset:1024
	s_waitcnt vmcnt(28)
	v_mfma_f32_16x16x32_bf16 v[6:9], v[82:85], v[86:89], v[6:9]
	v_mfma_f32_16x16x32_bf16 v[20:23], v[82:85], v[94:97], v[20:23]
	v_mfma_f32_16x16x32_bf16 v[24:27], v[90:93], v[86:89], v[24:27]
	v_mfma_f32_16x16x32_bf16 v[10:13], v[90:93], v[94:97], v[10:13]
	global_load_dwordx4 v[82:85], v[56:57], off offset:1088
	global_load_dwordx4 v[86:89], v[58:59], off offset:1088
	global_load_dwordx4 v[90:93], v[60:61], off offset:1088
	global_load_dwordx4 v[94:97], v[62:63], off offset:1088
	s_waitcnt vmcnt(28)
	v_mfma_f32_16x16x32_bf16 v[6:9], v[98:101], v[102:105], v[6:9]
	v_mfma_f32_16x16x32_bf16 v[20:23], v[98:101], v[110:113], v[20:23]
	v_mfma_f32_16x16x32_bf16 v[24:27], v[106:109], v[102:105], v[24:27]
	v_mfma_f32_16x16x32_bf16 v[10:13], v[106:109], v[110:113], v[10:13]
	global_load_dwordx4 v[98:101], v[56:57], off offset:1152
	global_load_dwordx4 v[102:105], v[58:59], off offset:1152
	global_load_dwordx4 v[106:109], v[60:61], off offset:1152
	global_load_dwordx4 v[110:113], v[62:63], off offset:1152
	s_waitcnt vmcnt(28)
	v_mfma_f32_16x16x32_bf16 v[6:9], v[114:117], v[118:121], v[6:9]
	v_mfma_f32_16x16x32_bf16 v[20:23], v[114:117], v[128:131], v[20:23]
	v_mfma_f32_16x16x32_bf16 v[24:27], v[122:125], v[118:121], v[24:27]
	v_mfma_f32_16x16x32_bf16 v[10:13], v[122:125], v[128:131], v[10:13]
	global_load_dwordx4 v[114:117], v[56:57], off offset:1216
	global_load_dwordx4 v[118:121], v[58:59], off offset:1216
	global_load_dwordx4 v[122:125], v[60:61], off offset:1216
	global_load_dwordx4 v[128:131], v[62:63], off offset:1216
	s_waitcnt vmcnt(28)
	v_mfma_f32_16x16x32_bf16 v[6:9], v[132:135], v[136:139], v[6:9]
	v_mfma_f32_16x16x32_bf16 v[20:23], v[132:135], v[144:147], v[20:23]
	v_mfma_f32_16x16x32_bf16 v[24:27], v[140:143], v[136:139], v[24:27]
	v_mfma_f32_16x16x32_bf16 v[10:13], v[140:143], v[144:147], v[10:13]
	global_load_dwordx4 v[132:135], v[56:57], off offset:1280
	global_load_dwordx4 v[136:139], v[58:59], off offset:1280
	global_load_dwordx4 v[140:143], v[60:61], off offset:1280
	global_load_dwordx4 v[144:147], v[62:63], off offset:1280
	s_waitcnt vmcnt(28)
	v_mfma_f32_16x16x32_bf16 v[6:9], v[148:151], v[170:173], v[6:9]
	v_mfma_f32_16x16x32_bf16 v[20:23], v[148:151], v[178:181], v[20:23]
	v_mfma_f32_16x16x32_bf16 v[24:27], v[174:177], v[170:173], v[24:27]
	v_mfma_f32_16x16x32_bf16 v[10:13], v[174:177], v[178:181], v[10:13]
	global_load_dwordx4 v[148:151], v[56:57], off offset:1344
	global_load_dwordx4 v[170:173], v[58:59], off offset:1344
	global_load_dwordx4 v[174:177], v[60:61], off offset:1344
	global_load_dwordx4 v[178:181], v[62:63], off offset:1344
	s_waitcnt vmcnt(28)
; __device__ __forceinline__ float bflo(unsigned w) { return __uint_as_float(w << 16); }
; template <int MODE>
; __device__ __forceinline__ void skinny_phase(const Params& P, unsigned char* shm) {
;     ...
; #pragma unroll 8
;         for (int ks = 0; ks < nks; ++ks) { const bf16x8 a0 = *(const bf16x8*)(ap + 32 * ks), a1 = *(const bf16x8*)(ap + (size_t)16 * ld + 32 * ks), b0 = *(const bf16x8*)(bp + 32 * ks), b1 = *(const bf16x8*)(bp + (size_t)16 * ld + 32 * ks);
;             acc[0][0] = mfma16(a0, b0, acc[0][0]); acc[0][1] = mfma16(a0, b1, acc[0][1]); acc[1][0] = mfma16(a1, b0, acc[1][0]); acc[1][1] = mfma16(a1, b1, acc[1][1]); }
;         MFMA_SETTLE();
; #pragma unroll
;         for (int mi = 0; mi < 2; ++mi)
; #pragma unroll
;             for (int ni = 0; ni < 2; ++ni)
; #pragma unroll
;                 for (int r = 0; r < 4; ++r) red[wave * 1024 + (16 * mi + 4 * q + r) * 32 + 16 * ni + l16] = acc[mi][ni][r];
;         __syncthreads();
;         { const int e = tid * 2, rr = e >> 5, cc = e & 31; const int row = ROW_S + 32 * mt + rr, col = 32 * nt + cc;
;           float s0 = 0.f, s1 = 0.f, u0 = 0.f, u1 = 0.f;
; #pragma unroll
;           for (int w = 0; w < 4; ++w) { const f32x2 x = *(const f32x2*)(red + w * 1024 + e), y = *(const f32x2*)(red + (4 + w) * 1024 + e); s0 += x.x; s1 += x.y; u0 += y.x; u1 += y.y; }
;           if (MODE == 0) { const bf16_t* gp = (const bf16_t*)(ws + O_PROJ) + (size_t)row * NPROJ + col;
;               const unsigned ga = *(const unsigned*)(gp + C_GA), gb = *(const unsigned*)(gp + C_GB);
;               const float m0 = sigmoidf_(bflo(ga)) * s0 + sigmoidf_(bflo(gb)) * u0, m1 = sigmoidf_(bfhi(ga)) * s1 + sigmoidf_(bfhi(gb)) * u1;
;               *(unsigned*)((bf16_t*)(ws + O_MIX) + (size_t)row * D + col) = cvt_pk_bf16(m0, m1); }
;           else if (MODE == 1) { const f32x2 xv = *(const f32x2*)(P.in[1] + (size_t)(row - ROW_S) * D + col);
;               *(unsigned*)((bf16_t*)(ws + O_R) + (size_t)row * D + col) = cvt_pk_bf16(ALPHA * xv.x + s0 + u0, ALPHA * xv.y + s1 + u1); }
;           else { const unsigned xw = *(const unsigned*)((const bf16_t*)(ws + O_X1B) + (size_t)row * D + col);
;               *(unsigned*)((bf16_t*)(ws + O_R) + (size_t)row * D + col) = cvt_pk_bf16(ALPHA * bflo(xw) + s0 + u0, ALPHA * bfhi(xw) + s1 + u1); } }
;         __syncthreads();
	v_mfma_f32_16x16x32_bf16 v[6:9], v[188:191], v[192:195], v[6:9]
	v_mfma_f32_16x16x32_bf16 v[20:23], v[188:191], v[200:203], v[20:23]
	v_mfma_f32_16x16x32_bf16 v[24:27], v[196:199], v[192:195], v[24:27]
	v_mfma_f32_16x16x32_bf16 v[10:13], v[196:199], v[200:203], v[10:13]
	s_waitcnt vmcnt(24)
	v_mfma_f32_16x16x32_bf16 v[6:9], v[204:207], v[208:211], v[6:9]
	v_mfma_f32_16x16x32_bf16 v[20:23], v[204:207], v[36:39], v[20:23]
	v_mfma_f32_16x16x32_bf16 v[24:27], v[32:35], v[208:211], v[24:27]
	v_mfma_f32_16x16x32_bf16 v[10:13], v[32:35], v[36:39], v[10:13]
	s_waitcnt vmcnt(20)
	v_mfma_f32_16x16x32_bf16 v[6:9], v[66:69], v[70:73], v[6:9]
	v_mfma_f32_16x16x32_bf16 v[20:23], v[66:69], v[78:81], v[20:23]
	v_mfma_f32_16x16x32_bf16 v[24:27], v[74:77], v[70:73], v[24:27]
	v_mfma_f32_16x16x32_bf16 v[10:13], v[74:77], v[78:81], v[10:13]
	s_waitcnt vmcnt(16)
	v_mfma_f32_16x16x32_bf16 v[6:9], v[82:85], v[86:89], v[6:9]
	v_mfma_f32_16x16x32_bf16 v[20:23], v[82:85], v[94:97], v[20:23]
	v_mfma_f32_16x16x32_bf16 v[24:27], v[90:93], v[86:89], v[24:27]
	v_mfma_f32_16x16x32_bf16 v[10:13], v[90:93], v[94:97], v[10:13]
	s_waitcnt vmcnt(12)
	v_mfma_f32_16x16x32_bf16 v[6:9], v[98:101], v[102:105], v[6:9]
	v_mfma_f32_16x16x32_bf16 v[20:23], v[98:101], v[110:113], v[20:23]
	v_mfma_f32_16x16x32_bf16 v[24:27], v[106:109], v[102:105], v[24:27]
	v_mfma_f32_16x16x32_bf16 v[10:13], v[106:109], v[110:113], v[10:13]
	s_waitcnt vmcnt(8)
	v_mfma_f32_16x16x32_bf16 v[6:9], v[114:117], v[118:121], v[6:9]
	v_mfma_f32_16x16x32_bf16 v[20:23], v[114:117], v[128:131], v[20:23]
	v_mfma_f32_16x16x32_bf16 v[24:27], v[122:125], v[118:121], v[24:27]
	v_mfma_f32_16x16x32_bf16 v[10:13], v[122:125], v[128:131], v[10:13]
	s_waitcnt vmcnt(4)
	v_mfma_f32_16x16x32_bf16 v[6:9], v[132:135], v[136:139], v[6:9]
	v_mfma_f32_16x16x32_bf16 v[20:23], v[132:135], v[144:147], v[20:23]
	v_mfma_f32_16x16x32_bf16 v[24:27], v[140:143], v[136:139], v[24:27]
	v_mfma_f32_16x16x32_bf16 v[10:13], v[140:143], v[144:147], v[10:13]
	s_waitcnt vmcnt(0)
	v_mfma_f32_16x16x32_bf16 v[6:9], v[148:151], v[170:173], v[6:9]
	v_mfma_f32_16x16x32_bf16 v[20:23], v[148:151], v[178:181], v[20:23]
	v_mfma_f32_16x16x32_bf16 v[24:27], v[174:177], v[170:173], v[24:27]
	v_mfma_f32_16x16x32_bf16 v[10:13], v[174:177], v[178:181], v[10:13]
	s_nop 15
	s_nop 15
	s_nop 5
	ds_write2_b32 v17, v6, v20 offset1:16
	ds_write2_b32 v17, v7, v21 offset0:32 offset1:48
	ds_write2_b32 v17, v8, v22 offset0:64 offset1:80
	ds_write2_b32 v17, v9, v23 offset0:96 offset1:112
	ds_write2_b32 v18, v24, v10 offset1:16
	ds_write2_b32 v18, v25, v11 offset0:32 offset1:48
	ds_write2_b32 v18, v26, v12 offset0:64 offset1:80
	ds_write2_b32 v18, v27, v13 offset0:96 offset1:112
	v_or_b32_e32 v6, s10, v15
	v_add_lshl_u32 v0, s9, v14, 12
	v_ashrrev_i32_e32 v7, 31, v6
	v_lshl_add_u64 v[8:9], s[12:13], 0, v[0:1]
	v_lshlrev_b64 v[28:29], 1, v[6:7]
	v_lshl_add_u64 v[6:7], v[8:9], 0, v[28:29]
	s_waitcnt lgkmcnt(0)
	s_barrier
	global_load_dword v19, v[6:7], off
	ds_read2st64_b64 v[6:9], v16 offset1:8
	ds_read2st64_b64 v[10:13], v16 offset0:32 offset1:40
	ds_read2st64_b64 v[20:23], v16 offset0:16 offset1:24
	ds_read2st64_b64 v[24:27], v16 offset0:48 offset1:56
	v_lshl_add_u64 v[30:31], s[6:7], 0, v[0:1]
	v_lshl_add_u64 v[28:29], v[30:31], 0, v[28:29]
	s_waitcnt lgkmcnt(2)
	v_mov_b32_e32 v30, v10
	v_mov_b32_e32 v31, v6
	v_mov_b32_e32 v32, v12
	v_mov_b32_e32 v33, v8
	v_mov_b32_e32 v6, v11
	v_pk_add_f32 v[10:11], v[30:31], 0 op_sel_hi:[1,0]
	s_waitcnt lgkmcnt(0)
	v_mov_b32_e32 v34, v24
	v_mov_b32_e32 v35, v20
	v_mov_b32_e32 v8, v13
	v_pk_add_f32 v[6:7], v[6:7], 0 op_sel_hi:[1,0]
	v_pk_add_f32 v[10:11], v[10:11], v[32:33]
	v_mov_b32_e32 v36, v26
	v_mov_b32_e32 v37, v22
	v_mov_b32_e32 v20, v25
	v_pk_add_f32 v[6:7], v[6:7], v[8:9]
	v_pk_add_f32 v[8:9], v[10:11], v[34:35]
	v_mov_b32_e32 v22, v27
	v_pk_add_f32 v[6:7], v[6:7], v[20:21]
	v_pk_add_f32 v[8:9], v[8:9], v[36:37]
	s_add_i32 s94, s94, s96
	s_add_i32 s2, s2, s3
	s_add_i32 s4, s4, s5
	v_pk_add_f32 v[6:7], v[6:7], v[22:23]
	s_cmpk_lt_i32 s94, 0x100
	s_waitcnt vmcnt(0)
	v_lshlrev_b32_e32 v0, 16, v19
	v_and_b32_e32 v10, 0xffff0000, v19
	v_fmamk_f32 v0, v0, 0x3f9837f0, v9
	v_fmamk_f32 v7, v10, 0x3f9837f0, v7
	v_add_f32_e32 v0, v8, v0
	v_add_f32_e32 v6, v6, v7
	v_cvt_pk_bf16_f32 v0, v0, v6
	global_store_dword v[28:29], v0, off
	s_barrier
	s_cbranch_scc1 .LBB0_1358
	s_bitcmp0_b32 s94, 3
	s_cbranch_scc1 .LBB0_1359
	s_and_b32 s94, s94, 0xff
	s_branch .Lp10_gemm
